# G2/F2 k-loops: first iteration of a tile uses vmcnt(24) at the S0 (and G2 S1) wait so the previous tile's epilogue stores need not retire before the first MMA segments (counted waits)
# speedup vs baseline: 1.0072x; 1.0032x over previous
.LBB0_650:
	s_add_u32 s2, s4, 0x100
	s_addc_u32 s3, s5, 0
	s_add_i32 s49, 0, 0x10000
	s_cmp_eq_u32 s48, 12
	s_cselect_b32 s29, s17, s3
	s_cselect_b32 s28, s25, s2
	v_add_u32_e32 v0, s49, v135
	s_cselect_b32 s27, s15, s47
	s_cselect_b32 s26, s42, s46
	s_add_i32 s50, 0, 0x14000
	ds_read_b128 v[146:149], v0
	ds_read_b128 v[150:153], v0 offset:1024
	ds_read_b128 v[154:157], v0 offset:2048
	ds_read_b128 v[158:161], v0 offset:3072
	v_add_u32_e32 v0, s50, v135
	ds_read_b128 v[162:165], v0
	ds_read_b128 v[166:169], v0 offset:1024
	ds_read_b128 v[170:173], v0 offset:2048
	ds_read_b128 v[174:177], v0 offset:3072
	v_lshl_add_u64 v[142:143], s[4:5], 0, v[138:139]
	s_add_i32 m0, s23, 0xc000
	ds_read_b128 v[178:181], v144
	ds_read_b128 v[182:185], v144 offset:1024
	ds_read_b128 v[186:189], v144 offset:2048
	ds_read_b128 v[190:193], v144 offset:3072
	ds_read_b128 v[194:197], v144 offset:4096
	ds_read_b128 v[198:201], v144 offset:5120
	ds_read_b128 v[202:205], v144 offset:6144
	ds_read_b128 v[222:225], v144 offset:7168
	global_load_lds_dwordx4 v[142:143], off
	v_lshl_add_u64 v[142:143], s[4:5], 0, v[140:141]
	s_add_i32 m0, s23, 0xe000
	s_nop 0
	global_load_lds_dwordx4 v[142:143], off
	s_cmp_lg_u32 s48, -2
	s_cbranch_scc1 .Lsw_g20a
	s_waitcnt vmcnt(24)
	s_branch .Lsw_g20b
.Lsw_g20a:
	s_waitcnt vmcnt(8)
.Lsw_g20b:
	s_waitcnt lgkmcnt(0)
	s_setprio 1
	s_barrier
	v_mfma_f32_16x16x32_bf16 v[126:129], v[146:149], v[178:181], v[126:129]
	v_mfma_f32_16x16x32_bf16 v[122:125], v[154:157], v[178:181], v[122:125]
	v_mfma_f32_16x16x32_bf16 v[110:113], v[146:149], v[186:189], v[110:113]
	v_mfma_f32_16x16x32_bf16 v[106:109], v[154:157], v[186:189], v[106:109]
	v_mfma_f32_16x16x32_bf16 v[94:97], v[146:149], v[194:197], v[94:97]
	v_mfma_f32_16x16x32_bf16 v[90:93], v[154:157], v[194:197], v[90:93]
	v_mfma_f32_16x16x32_bf16 v[78:81], v[146:149], v[202:205], v[78:81]
	v_mfma_f32_16x16x32_bf16 v[74:77], v[154:157], v[202:205], v[74:77]
	v_mfma_f32_16x16x32_bf16 v[126:129], v[150:153], v[182:185], v[126:129]
	v_mfma_f32_16x16x32_bf16 v[122:125], v[158:161], v[182:185], v[122:125]
	v_mfma_f32_16x16x32_bf16 v[110:113], v[150:153], v[190:193], v[110:113]
	v_mfma_f32_16x16x32_bf16 v[106:109], v[158:161], v[190:193], v[106:109]
	v_mfma_f32_16x16x32_bf16 v[94:97], v[150:153], v[198:201], v[94:97]
	v_mfma_f32_16x16x32_bf16 v[90:93], v[158:161], v[198:201], v[90:93]
	v_mfma_f32_16x16x32_bf16 v[78:81], v[150:153], v[222:225], v[78:81]
	v_mfma_f32_16x16x32_bf16 v[74:77], v[158:161], v[222:225], v[74:77]
	v_mfma_f32_16x16x32_bf16 v[118:121], v[162:165], v[178:181], v[118:121]
	v_mfma_f32_16x16x32_bf16 v[114:117], v[170:173], v[178:181], v[114:117]
	v_mfma_f32_16x16x32_bf16 v[102:105], v[162:165], v[186:189], v[102:105]
	v_mfma_f32_16x16x32_bf16 v[98:101], v[170:173], v[186:189], v[98:101]
	v_mfma_f32_16x16x32_bf16 v[86:89], v[162:165], v[194:197], v[86:89]
	v_mfma_f32_16x16x32_bf16 v[82:85], v[170:173], v[194:197], v[82:85]
	v_mfma_f32_16x16x32_bf16 v[70:73], v[162:165], v[202:205], v[70:73]
	v_mfma_f32_16x16x32_bf16 v[66:69], v[170:173], v[202:205], v[66:69]
	v_mfma_f32_16x16x32_bf16 v[118:121], v[166:169], v[182:185], v[118:121]
	v_mfma_f32_16x16x32_bf16 v[114:117], v[174:177], v[182:185], v[114:117]
	v_mfma_f32_16x16x32_bf16 v[102:105], v[166:169], v[190:193], v[102:105]
	v_mfma_f32_16x16x32_bf16 v[98:101], v[174:177], v[190:193], v[98:101]
	v_mfma_f32_16x16x32_bf16 v[86:89], v[166:169], v[198:201], v[86:89]
	v_mfma_f32_16x16x32_bf16 v[82:85], v[174:177], v[198:201], v[82:85]
	v_mfma_f32_16x16x32_bf16 v[70:73], v[166:169], v[222:225], v[70:73]
	v_mfma_f32_16x16x32_bf16 v[66:69], v[174:177], v[222:225], v[66:69]
	s_barrier
	s_setprio 0
	s_add_i32 s4, s49, s30
	v_lshl_add_u64 v[142:143], s[26:27], 0, v[130:131]
	s_mov_b32 m0, s4
	ds_read_b128 v[178:181], v144 offset:16384
	ds_read_b128 v[182:185], v144 offset:17408
	ds_read_b128 v[186:189], v144 offset:18432
	ds_read_b128 v[190:193], v144 offset:19456
	ds_read_b128 v[194:197], v144 offset:20480
	ds_read_b128 v[198:201], v144 offset:21504
	ds_read_b128 v[202:205], v144 offset:22528
	ds_read_b128 v[222:225], v144 offset:23552
	global_load_lds_dwordx4 v[142:143], off
	s_add_i32 m0, s4, 0x2000
	s_add_u32 s4, s26, 0x40000
	v_lshl_add_u64 v[206:207], s[26:27], 0, v[132:133]
	s_addc_u32 s5, s27, 0
	s_add_i32 s49, s50, s30
	global_load_lds_dwordx4 v[206:207], off
	v_lshl_add_u64 v[218:219], s[4:5], 0, v[130:131]
	s_mov_b32 m0, s49
	v_lshl_add_u64 v[226:227], s[28:29], 0, v[132:133]
	global_load_lds_dwordx4 v[218:219], off
	v_lshl_add_u64 v[218:219], s[4:5], 0, v[132:133]
	s_add_i32 m0, s49, 0x2000
	s_nop 0
	global_load_lds_dwordx4 v[218:219], off
	v_lshl_add_u64 v[218:219], s[28:29], 0, v[130:131]
	s_mov_b32 m0, s23
	s_nop 0
	global_load_lds_dwordx4 v[218:219], off
	s_mov_b32 m0, s31
	s_nop 0
	global_load_lds_dwordx4 v[226:227], off
	s_cmp_lg_u32 s48, -2
	s_cbranch_scc1 .Lsw_g21a
	s_waitcnt vmcnt(24)
	s_branch .Lsw_g21b

.Lsw_g21b:
	s_waitcnt lgkmcnt(0)
	s_setprio 1
	s_barrier
	v_mfma_f32_16x16x32_bf16 v[62:65], v[146:149], v[178:181], v[62:65]
	v_mfma_f32_16x16x32_bf16 v[58:61], v[154:157], v[178:181], v[58:61]
	v_mfma_f32_16x16x32_bf16 v[46:49], v[146:149], v[186:189], v[46:49]
	v_mfma_f32_16x16x32_bf16 v[42:45], v[154:157], v[186:189], v[42:45]
	v_mfma_f32_16x16x32_bf16 v[30:33], v[146:149], v[194:197], v[30:33]
	v_mfma_f32_16x16x32_bf16 v[26:29], v[154:157], v[194:197], v[26:29]
	v_mfma_f32_16x16x32_bf16 v[14:17], v[146:149], v[202:205], v[14:17]
	v_mfma_f32_16x16x32_bf16 v[10:13], v[154:157], v[202:205], v[10:13]
	v_mfma_f32_16x16x32_bf16 v[62:65], v[150:153], v[182:185], v[62:65]
	v_mfma_f32_16x16x32_bf16 v[58:61], v[158:161], v[182:185], v[58:61]
	v_mfma_f32_16x16x32_bf16 v[46:49], v[150:153], v[190:193], v[46:49]
	v_mfma_f32_16x16x32_bf16 v[42:45], v[158:161], v[190:193], v[42:45]
	v_mfma_f32_16x16x32_bf16 v[30:33], v[150:153], v[198:201], v[30:33]
	v_mfma_f32_16x16x32_bf16 v[26:29], v[158:161], v[198:201], v[26:29]
	v_mfma_f32_16x16x32_bf16 v[14:17], v[150:153], v[222:225], v[14:17]
	v_mfma_f32_16x16x32_bf16 v[10:13], v[158:161], v[222:225], v[10:13]
	v_mfma_f32_16x16x32_bf16 v[54:57], v[162:165], v[178:181], v[54:57]
	v_mfma_f32_16x16x32_bf16 v[50:53], v[170:173], v[178:181], v[50:53]
	v_mfma_f32_16x16x32_bf16 v[38:41], v[162:165], v[186:189], v[38:41]
	v_mfma_f32_16x16x32_bf16 v[34:37], v[170:173], v[186:189], v[34:37]
	v_mfma_f32_16x16x32_bf16 v[22:25], v[162:165], v[194:197], v[22:25]
	v_mfma_f32_16x16x32_bf16 v[18:21], v[170:173], v[194:197], v[18:21]
	v_mfma_f32_16x16x32_bf16 v[6:9], v[162:165], v[202:205], v[6:9]
	v_mfma_f32_16x16x32_bf16 v[2:5], v[170:173], v[202:205], v[2:5]
	v_mfma_f32_16x16x32_bf16 v[54:57], v[166:169], v[182:185], v[54:57]
	v_mfma_f32_16x16x32_bf16 v[50:53], v[174:177], v[182:185], v[50:53]
	v_mfma_f32_16x16x32_bf16 v[38:41], v[166:169], v[190:193], v[38:41]
	v_mfma_f32_16x16x32_bf16 v[34:37], v[174:177], v[190:193], v[34:37]
	v_mfma_f32_16x16x32_bf16 v[22:25], v[166:169], v[198:201], v[22:25]
	v_mfma_f32_16x16x32_bf16 v[18:21], v[174:177], v[198:201], v[18:21]
	v_mfma_f32_16x16x32_bf16 v[6:9], v[166:169], v[222:225], v[6:9]
	v_mfma_f32_16x16x32_bf16 v[2:5], v[174:177], v[222:225], v[2:5]
	s_barrier
	s_setprio 0
	s_add_i32 s49, 0, 0x18000
	v_add_u32_e32 v0, s49, v135
	s_add_i32 s50, 0, 0x1c000
	ds_read_b128 v[146:149], v0
	ds_read_b128 v[150:153], v0 offset:1024
	ds_read_b128 v[154:157], v0 offset:2048
	ds_read_b128 v[158:161], v0 offset:3072
	v_add_u32_e32 v0, s50, v135
	ds_read_b128 v[162:165], v0
	ds_read_b128 v[166:169], v0 offset:1024
	ds_read_b128 v[170:173], v0 offset:2048
	ds_read_b128 v[174:177], v0 offset:3072
	s_add_u32 s4, s28, 0x40000
	s_addc_u32 s5, s29, 0
	s_mov_b32 m0, s33
	v_lshl_add_u64 v[228:229], s[4:5], 0, v[130:131]
	ds_read_b128 v[178:181], v144 offset:32768
	ds_read_b128 v[182:185], v144 offset:33792
	ds_read_b128 v[186:189], v144 offset:34816
	ds_read_b128 v[190:193], v144 offset:35840
	ds_read_b128 v[194:197], v144 offset:36864
	ds_read_b128 v[198:201], v144 offset:37888
	ds_read_b128 v[202:205], v144 offset:38912
	ds_read_b128 v[222:225], v144 offset:39936
	global_load_lds_dwordx4 v[228:229], off
	v_lshl_add_u64 v[228:229], s[4:5], 0, v[132:133]
	s_mov_b32 m0, s34
	s_nop 0
	global_load_lds_dwordx4 v[228:229], off
	s_waitcnt vmcnt(8)
	s_waitcnt lgkmcnt(0)
	s_setprio 1
	s_barrier
	v_mfma_f32_16x16x32_bf16 v[126:129], v[146:149], v[178:181], v[126:129]
	v_mfma_f32_16x16x32_bf16 v[122:125], v[154:157], v[178:181], v[122:125]
	v_mfma_f32_16x16x32_bf16 v[110:113], v[146:149], v[186:189], v[110:113]
	v_mfma_f32_16x16x32_bf16 v[106:109], v[154:157], v[186:189], v[106:109]
	v_mfma_f32_16x16x32_bf16 v[94:97], v[146:149], v[194:197], v[94:97]
	v_mfma_f32_16x16x32_bf16 v[90:93], v[154:157], v[194:197], v[90:93]
	v_mfma_f32_16x16x32_bf16 v[78:81], v[146:149], v[202:205], v[78:81]
	v_mfma_f32_16x16x32_bf16 v[74:77], v[154:157], v[202:205], v[74:77]
	v_mfma_f32_16x16x32_bf16 v[126:129], v[150:153], v[182:185], v[126:129]
	v_mfma_f32_16x16x32_bf16 v[122:125], v[158:161], v[182:185], v[122:125]
	v_mfma_f32_16x16x32_bf16 v[110:113], v[150:153], v[190:193], v[110:113]
	v_mfma_f32_16x16x32_bf16 v[106:109], v[158:161], v[190:193], v[106:109]
	v_mfma_f32_16x16x32_bf16 v[94:97], v[150:153], v[198:201], v[94:97]
	v_mfma_f32_16x16x32_bf16 v[90:93], v[158:161], v[198:201], v[90:93]
	v_mfma_f32_16x16x32_bf16 v[78:81], v[150:153], v[222:225], v[78:81]
	v_mfma_f32_16x16x32_bf16 v[74:77], v[158:161], v[222:225], v[74:77]
	v_mfma_f32_16x16x32_bf16 v[118:121], v[162:165], v[178:181], v[118:121]
	v_mfma_f32_16x16x32_bf16 v[114:117], v[170:173], v[178:181], v[114:117]
	v_mfma_f32_16x16x32_bf16 v[102:105], v[162:165], v[186:189], v[102:105]
	v_mfma_f32_16x16x32_bf16 v[98:101], v[170:173], v[186:189], v[98:101]
	v_mfma_f32_16x16x32_bf16 v[86:89], v[162:165], v[194:197], v[86:89]
	v_mfma_f32_16x16x32_bf16 v[82:85], v[170:173], v[194:197], v[82:85]
	v_mfma_f32_16x16x32_bf16 v[70:73], v[162:165], v[202:205], v[70:73]
	v_mfma_f32_16x16x32_bf16 v[66:69], v[170:173], v[202:205], v[66:69]
	v_mfma_f32_16x16x32_bf16 v[118:121], v[166:169], v[182:185], v[118:121]
	v_mfma_f32_16x16x32_bf16 v[114:117], v[174:177], v[182:185], v[114:117]
	v_mfma_f32_16x16x32_bf16 v[102:105], v[166:169], v[190:193], v[102:105]
	v_mfma_f32_16x16x32_bf16 v[98:101], v[174:177], v[190:193], v[98:101]
	v_mfma_f32_16x16x32_bf16 v[86:89], v[166:169], v[198:201], v[86:89]
	v_mfma_f32_16x16x32_bf16 v[82:85], v[174:177], v[198:201], v[82:85]
	v_mfma_f32_16x16x32_bf16 v[70:73], v[166:169], v[222:225], v[70:73]
	v_mfma_f32_16x16x32_bf16 v[66:69], v[174:177], v[222:225], v[66:69]
	s_barrier
	s_setprio 0
	s_add_i32 s4, s49, s30
	v_lshl_add_u64 v[142:143], v[142:143], 0, s[44:45]
	s_mov_b32 m0, s4
	ds_read_b128 v[178:181], v144 offset:49152
	ds_read_b128 v[182:185], v144 offset:50176
	ds_read_b128 v[186:189], v144 offset:51200
	ds_read_b128 v[190:193], v144 offset:52224
	ds_read_b128 v[194:197], v144 offset:53248
	ds_read_b128 v[198:201], v144 offset:54272
	ds_read_b128 v[202:205], v144 offset:55296
	ds_read_b128 v[222:225], v144 offset:56320
	global_load_lds_dwordx4 v[142:143], off
	s_add_i32 m0, s4, 0x2000
	s_add_u32 s4, s26, 0x40080
	v_lshl_add_u64 v[142:143], v[206:207], 0, s[44:45]
	s_addc_u32 s5, s27, 0
	s_add_i32 s26, s50, s30
	global_load_lds_dwordx4 v[142:143], off
	v_lshl_add_u64 v[142:143], s[4:5], 0, v[130:131]
	s_mov_b32 m0, s26
	s_nop 0
	global_load_lds_dwordx4 v[142:143], off
	v_lshl_add_u64 v[142:143], s[4:5], 0, v[132:133]
	s_add_i32 m0, s26, 0x2000
	s_nop 0
	global_load_lds_dwordx4 v[142:143], off
	v_lshl_add_u64 v[142:143], v[218:219], 0, s[44:45]
	s_mov_b32 m0, s37
	s_nop 0
	global_load_lds_dwordx4 v[142:143], off
	v_lshl_add_u64 v[142:143], v[226:227], 0, s[44:45]
	s_mov_b32 m0, s38
	s_nop 0
	global_load_lds_dwordx4 v[142:143], off
	s_waitcnt vmcnt(8)
	s_waitcnt lgkmcnt(0)
	s_setprio 1
	s_barrier
	v_mfma_f32_16x16x32_bf16 v[62:65], v[146:149], v[178:181], v[62:65]
	v_mfma_f32_16x16x32_bf16 v[58:61], v[154:157], v[178:181], v[58:61]
	v_mfma_f32_16x16x32_bf16 v[46:49], v[146:149], v[186:189], v[46:49]
	v_mfma_f32_16x16x32_bf16 v[42:45], v[154:157], v[186:189], v[42:45]
	v_mfma_f32_16x16x32_bf16 v[30:33], v[146:149], v[194:197], v[30:33]
	v_mfma_f32_16x16x32_bf16 v[26:29], v[154:157], v[194:197], v[26:29]
	v_mfma_f32_16x16x32_bf16 v[14:17], v[146:149], v[202:205], v[14:17]
	v_mfma_f32_16x16x32_bf16 v[10:13], v[154:157], v[202:205], v[10:13]
	v_mfma_f32_16x16x32_bf16 v[62:65], v[150:153], v[182:185], v[62:65]
	v_mfma_f32_16x16x32_bf16 v[58:61], v[158:161], v[182:185], v[58:61]
	v_mfma_f32_16x16x32_bf16 v[46:49], v[150:153], v[190:193], v[46:49]
	v_mfma_f32_16x16x32_bf16 v[42:45], v[158:161], v[190:193], v[42:45]
	v_mfma_f32_16x16x32_bf16 v[30:33], v[150:153], v[198:201], v[30:33]
	v_mfma_f32_16x16x32_bf16 v[26:29], v[158:161], v[198:201], v[26:29]
	v_mfma_f32_16x16x32_bf16 v[14:17], v[150:153], v[222:225], v[14:17]
	v_mfma_f32_16x16x32_bf16 v[10:13], v[158:161], v[222:225], v[10:13]
	v_mfma_f32_16x16x32_bf16 v[54:57], v[162:165], v[178:181], v[54:57]
	v_mfma_f32_16x16x32_bf16 v[50:53], v[170:173], v[178:181], v[50:53]
	v_mfma_f32_16x16x32_bf16 v[38:41], v[162:165], v[186:189], v[38:41]
	v_mfma_f32_16x16x32_bf16 v[34:37], v[170:173], v[186:189], v[34:37]
	v_mfma_f32_16x16x32_bf16 v[22:25], v[162:165], v[194:197], v[22:25]
	v_mfma_f32_16x16x32_bf16 v[18:21], v[170:173], v[194:197], v[18:21]
	v_mfma_f32_16x16x32_bf16 v[6:9], v[162:165], v[202:205], v[6:9]
	v_mfma_f32_16x16x32_bf16 v[2:5], v[170:173], v[202:205], v[2:5]
	v_mfma_f32_16x16x32_bf16 v[54:57], v[166:169], v[182:185], v[54:57]
	v_mfma_f32_16x16x32_bf16 v[50:53], v[174:177], v[182:185], v[50:53]
	v_mfma_f32_16x16x32_bf16 v[38:41], v[166:169], v[190:193], v[38:41]
	v_mfma_f32_16x16x32_bf16 v[34:37], v[174:177], v[190:193], v[34:37]
	v_mfma_f32_16x16x32_bf16 v[22:25], v[166:169], v[198:201], v[22:25]
	v_mfma_f32_16x16x32_bf16 v[18:21], v[174:177], v[198:201], v[18:21]
	v_mfma_f32_16x16x32_bf16 v[6:9], v[166:169], v[222:225], v[6:9]
	v_mfma_f32_16x16x32_bf16 v[2:5], v[174:177], v[222:225], v[2:5]
	s_barrier
	s_setprio 0
	s_add_i32 s48, s48, 2
	s_add_u32 s46, s46, 0x100
	s_addc_u32 s47, s47, 0
	s_cmp_gt_u32 s48, 13
	s_mov_b64 s[4:5], s[2:3]
	s_cbranch_scc0 .LBB0_650
	s_and_b64 vcc, exec, s[12:13]
	s_cbranch_vccz .LBB0_653
	s_barrier

.LBB0_849:
	s_add_u32 s2, s18, 0x100
	s_addc_u32 s3, s19, 0
	s_add_i32 s47, 0, 0x10000
	s_cmp_eq_u32 s46, 40
	s_cselect_b32 s23, s9, s3
	s_cselect_b32 s22, s8, s2
	v_add_u32_e32 v0, s47, v135
	s_cselect_b32 s21, s15, s42
	s_cselect_b32 s20, s14, s17
	s_add_i32 s48, 0, 0x14000
	ds_read_b128 v[146:149], v0
	ds_read_b128 v[150:153], v0 offset:1024
	ds_read_b128 v[154:157], v0 offset:2048
	ds_read_b128 v[158:161], v0 offset:3072
	v_add_u32_e32 v0, s48, v135
	ds_read_b128 v[162:165], v0
	ds_read_b128 v[166:169], v0 offset:1024
	ds_read_b128 v[170:173], v0 offset:2048
	ds_read_b128 v[174:177], v0 offset:3072
	v_lshl_add_u64 v[142:143], s[18:19], 0, v[138:139]
	s_add_i32 m0, s25, 0xc000
	ds_read_b128 v[178:181], v144
	ds_read_b128 v[182:185], v144 offset:1024
	ds_read_b128 v[186:189], v144 offset:2048
	ds_read_b128 v[190:193], v144 offset:3072
	ds_read_b128 v[194:197], v144 offset:4096
	ds_read_b128 v[198:201], v144 offset:5120
	ds_read_b128 v[202:205], v144 offset:6144
	ds_read_b128 v[222:225], v144 offset:7168
	global_load_lds_dwordx4 v[142:143], off
	v_lshl_add_u64 v[142:143], s[18:19], 0, v[140:141]
	s_add_i32 m0, s25, 0xe000
	s_nop 0
	global_load_lds_dwordx4 v[142:143], off
	s_cmp_lg_u32 s46, -2
	s_cbranch_scc1 .Lsw_f20a
	s_waitcnt vmcnt(24)
	s_branch .Lsw_f20b

.Lsw_f20b:
	s_waitcnt lgkmcnt(0)
	s_setprio 1
	s_barrier
	v_mfma_f32_16x16x32_bf16 v[126:129], v[146:149], v[178:181], v[126:129]
	v_mfma_f32_16x16x32_bf16 v[122:125], v[154:157], v[178:181], v[122:125]
	v_mfma_f32_16x16x32_bf16 v[110:113], v[146:149], v[186:189], v[110:113]
	v_mfma_f32_16x16x32_bf16 v[106:109], v[154:157], v[186:189], v[106:109]
	v_mfma_f32_16x16x32_bf16 v[94:97], v[146:149], v[194:197], v[94:97]
	v_mfma_f32_16x16x32_bf16 v[90:93], v[154:157], v[194:197], v[90:93]
	v_mfma_f32_16x16x32_bf16 v[78:81], v[146:149], v[202:205], v[78:81]
	v_mfma_f32_16x16x32_bf16 v[74:77], v[154:157], v[202:205], v[74:77]
	v_mfma_f32_16x16x32_bf16 v[126:129], v[150:153], v[182:185], v[126:129]
	v_mfma_f32_16x16x32_bf16 v[122:125], v[158:161], v[182:185], v[122:125]
	v_mfma_f32_16x16x32_bf16 v[110:113], v[150:153], v[190:193], v[110:113]
	v_mfma_f32_16x16x32_bf16 v[106:109], v[158:161], v[190:193], v[106:109]
	v_mfma_f32_16x16x32_bf16 v[94:97], v[150:153], v[198:201], v[94:97]
	v_mfma_f32_16x16x32_bf16 v[90:93], v[158:161], v[198:201], v[90:93]
	v_mfma_f32_16x16x32_bf16 v[78:81], v[150:153], v[222:225], v[78:81]
	v_mfma_f32_16x16x32_bf16 v[74:77], v[158:161], v[222:225], v[74:77]
	v_mfma_f32_16x16x32_bf16 v[118:121], v[162:165], v[178:181], v[118:121]
	v_mfma_f32_16x16x32_bf16 v[114:117], v[170:173], v[178:181], v[114:117]
	v_mfma_f32_16x16x32_bf16 v[102:105], v[162:165], v[186:189], v[102:105]
	v_mfma_f32_16x16x32_bf16 v[98:101], v[170:173], v[186:189], v[98:101]
	v_mfma_f32_16x16x32_bf16 v[86:89], v[162:165], v[194:197], v[86:89]
	v_mfma_f32_16x16x32_bf16 v[82:85], v[170:173], v[194:197], v[82:85]
	v_mfma_f32_16x16x32_bf16 v[70:73], v[162:165], v[202:205], v[70:73]
	v_mfma_f32_16x16x32_bf16 v[66:69], v[170:173], v[202:205], v[66:69]
	v_mfma_f32_16x16x32_bf16 v[118:121], v[166:169], v[182:185], v[118:121]
	v_mfma_f32_16x16x32_bf16 v[114:117], v[174:177], v[182:185], v[114:117]
	v_mfma_f32_16x16x32_bf16 v[102:105], v[166:169], v[190:193], v[102:105]
	v_mfma_f32_16x16x32_bf16 v[98:101], v[174:177], v[190:193], v[98:101]
	v_mfma_f32_16x16x32_bf16 v[86:89], v[166:169], v[198:201], v[86:89]
	v_mfma_f32_16x16x32_bf16 v[82:85], v[174:177], v[198:201], v[82:85]
	v_mfma_f32_16x16x32_bf16 v[70:73], v[166:169], v[222:225], v[70:73]
	v_mfma_f32_16x16x32_bf16 v[66:69], v[174:177], v[222:225], v[66:69]
	s_barrier
	s_setprio 0
	s_add_i32 s18, s47, s24
	v_lshl_add_u64 v[142:143], s[20:21], 0, v[130:131]
	s_mov_b32 m0, s18
	ds_read_b128 v[178:181], v144 offset:16384
	ds_read_b128 v[182:185], v144 offset:17408
	ds_read_b128 v[186:189], v144 offset:18432
	ds_read_b128 v[190:193], v144 offset:19456
	ds_read_b128 v[194:197], v144 offset:20480
	ds_read_b128 v[198:201], v144 offset:21504
	ds_read_b128 v[202:205], v144 offset:22528
	ds_read_b128 v[222:225], v144 offset:23552
	global_load_lds_dwordx4 v[142:143], off
	s_add_i32 m0, s18, 0x2000
	s_add_u32 s18, s20, 0xb0000
	v_lshl_add_u64 v[206:207], s[20:21], 0, v[132:133]
	s_addc_u32 s19, s21, 0
	s_add_i32 s47, s48, s24
	global_load_lds_dwordx4 v[206:207], off
	v_lshl_add_u64 v[218:219], s[18:19], 0, v[130:131]
	s_mov_b32 m0, s47
	v_lshl_add_u64 v[226:227], s[22:23], 0, v[132:133]
	global_load_lds_dwordx4 v[218:219], off
	v_lshl_add_u64 v[218:219], s[18:19], 0, v[132:133]
	s_add_i32 m0, s47, 0x2000
	s_nop 0
	global_load_lds_dwordx4 v[218:219], off
	v_lshl_add_u64 v[218:219], s[22:23], 0, v[130:131]
	s_mov_b32 m0, s25
	s_nop 0
	global_load_lds_dwordx4 v[218:219], off
	s_mov_b32 m0, s26
	s_nop 0
	global_load_lds_dwordx4 v[226:227], off
	s_waitcnt vmcnt(8)
	s_waitcnt lgkmcnt(0)
	s_setprio 1
	s_barrier
	v_mfma_f32_16x16x32_bf16 v[62:65], v[146:149], v[178:181], v[62:65]
	v_mfma_f32_16x16x32_bf16 v[58:61], v[154:157], v[178:181], v[58:61]
	v_mfma_f32_16x16x32_bf16 v[46:49], v[146:149], v[186:189], v[46:49]
	v_mfma_f32_16x16x32_bf16 v[42:45], v[154:157], v[186:189], v[42:45]
	v_mfma_f32_16x16x32_bf16 v[30:33], v[146:149], v[194:197], v[30:33]
	v_mfma_f32_16x16x32_bf16 v[26:29], v[154:157], v[194:197], v[26:29]
	v_mfma_f32_16x16x32_bf16 v[14:17], v[146:149], v[202:205], v[14:17]
	v_mfma_f32_16x16x32_bf16 v[10:13], v[154:157], v[202:205], v[10:13]
	v_mfma_f32_16x16x32_bf16 v[62:65], v[150:153], v[182:185], v[62:65]
	v_mfma_f32_16x16x32_bf16 v[58:61], v[158:161], v[182:185], v[58:61]
	v_mfma_f32_16x16x32_bf16 v[46:49], v[150:153], v[190:193], v[46:49]
	v_mfma_f32_16x16x32_bf16 v[42:45], v[158:161], v[190:193], v[42:45]
	v_mfma_f32_16x16x32_bf16 v[30:33], v[150:153], v[198:201], v[30:33]
	v_mfma_f32_16x16x32_bf16 v[26:29], v[158:161], v[198:201], v[26:29]
	v_mfma_f32_16x16x32_bf16 v[14:17], v[150:153], v[222:225], v[14:17]
	v_mfma_f32_16x16x32_bf16 v[10:13], v[158:161], v[222:225], v[10:13]
	v_mfma_f32_16x16x32_bf16 v[54:57], v[162:165], v[178:181], v[54:57]
	v_mfma_f32_16x16x32_bf16 v[50:53], v[170:173], v[178:181], v[50:53]
	v_mfma_f32_16x16x32_bf16 v[38:41], v[162:165], v[186:189], v[38:41]
	v_mfma_f32_16x16x32_bf16 v[34:37], v[170:173], v[186:189], v[34:37]
	v_mfma_f32_16x16x32_bf16 v[22:25], v[162:165], v[194:197], v[22:25]
	v_mfma_f32_16x16x32_bf16 v[18:21], v[170:173], v[194:197], v[18:21]
	v_mfma_f32_16x16x32_bf16 v[6:9], v[162:165], v[202:205], v[6:9]
	v_mfma_f32_16x16x32_bf16 v[2:5], v[170:173], v[202:205], v[2:5]
	v_mfma_f32_16x16x32_bf16 v[54:57], v[166:169], v[182:185], v[54:57]
	v_mfma_f32_16x16x32_bf16 v[50:53], v[174:177], v[182:185], v[50:53]
	v_mfma_f32_16x16x32_bf16 v[38:41], v[166:169], v[190:193], v[38:41]
	v_mfma_f32_16x16x32_bf16 v[34:37], v[174:177], v[190:193], v[34:37]
	v_mfma_f32_16x16x32_bf16 v[22:25], v[166:169], v[198:201], v[22:25]
	v_mfma_f32_16x16x32_bf16 v[18:21], v[174:177], v[198:201], v[18:21]
	v_mfma_f32_16x16x32_bf16 v[6:9], v[166:169], v[222:225], v[6:9]
	v_mfma_f32_16x16x32_bf16 v[2:5], v[174:177], v[222:225], v[2:5]
	s_barrier
	s_setprio 0
	s_add_i32 s47, 0, 0x18000
	v_add_u32_e32 v0, s47, v135
	s_add_i32 s48, 0, 0x1c000
	ds_read_b128 v[146:149], v0
	ds_read_b128 v[150:153], v0 offset:1024
	ds_read_b128 v[154:157], v0 offset:2048
	ds_read_b128 v[158:161], v0 offset:3072
	v_add_u32_e32 v0, s48, v135
	ds_read_b128 v[162:165], v0
	ds_read_b128 v[166:169], v0 offset:1024
	ds_read_b128 v[170:173], v0 offset:2048
	ds_read_b128 v[174:177], v0 offset:3072
	s_add_u32 s18, s22, 0xb0000
	s_addc_u32 s19, s23, 0
	s_mov_b32 m0, s27
	v_lshl_add_u64 v[228:229], s[18:19], 0, v[130:131]
	ds_read_b128 v[178:181], v144 offset:32768
	ds_read_b128 v[182:185], v144 offset:33792
	ds_read_b128 v[186:189], v144 offset:34816
	ds_read_b128 v[190:193], v144 offset:35840
	ds_read_b128 v[194:197], v144 offset:36864
	ds_read_b128 v[198:201], v144 offset:37888
	ds_read_b128 v[202:205], v144 offset:38912
	ds_read_b128 v[222:225], v144 offset:39936
	global_load_lds_dwordx4 v[228:229], off
	v_lshl_add_u64 v[228:229], s[18:19], 0, v[132:133]
	s_mov_b32 m0, s28
	s_nop 0
	global_load_lds_dwordx4 v[228:229], off
	s_waitcnt vmcnt(8)
	s_waitcnt lgkmcnt(0)
	s_setprio 1
	s_barrier
	v_mfma_f32_16x16x32_bf16 v[126:129], v[146:149], v[178:181], v[126:129]
	v_mfma_f32_16x16x32_bf16 v[122:125], v[154:157], v[178:181], v[122:125]
	v_mfma_f32_16x16x32_bf16 v[110:113], v[146:149], v[186:189], v[110:113]
	v_mfma_f32_16x16x32_bf16 v[106:109], v[154:157], v[186:189], v[106:109]
	v_mfma_f32_16x16x32_bf16 v[94:97], v[146:149], v[194:197], v[94:97]
	v_mfma_f32_16x16x32_bf16 v[90:93], v[154:157], v[194:197], v[90:93]
	v_mfma_f32_16x16x32_bf16 v[78:81], v[146:149], v[202:205], v[78:81]
	v_mfma_f32_16x16x32_bf16 v[74:77], v[154:157], v[202:205], v[74:77]
	v_mfma_f32_16x16x32_bf16 v[126:129], v[150:153], v[182:185], v[126:129]
	v_mfma_f32_16x16x32_bf16 v[122:125], v[158:161], v[182:185], v[122:125]
	v_mfma_f32_16x16x32_bf16 v[110:113], v[150:153], v[190:193], v[110:113]
	v_mfma_f32_16x16x32_bf16 v[106:109], v[158:161], v[190:193], v[106:109]
	v_mfma_f32_16x16x32_bf16 v[94:97], v[150:153], v[198:201], v[94:97]
	v_mfma_f32_16x16x32_bf16 v[90:93], v[158:161], v[198:201], v[90:93]
	v_mfma_f32_16x16x32_bf16 v[78:81], v[150:153], v[222:225], v[78:81]
	v_mfma_f32_16x16x32_bf16 v[74:77], v[158:161], v[222:225], v[74:77]
	v_mfma_f32_16x16x32_bf16 v[118:121], v[162:165], v[178:181], v[118:121]
	v_mfma_f32_16x16x32_bf16 v[114:117], v[170:173], v[178:181], v[114:117]
	v_mfma_f32_16x16x32_bf16 v[102:105], v[162:165], v[186:189], v[102:105]
	v_mfma_f32_16x16x32_bf16 v[98:101], v[170:173], v[186:189], v[98:101]
	v_mfma_f32_16x16x32_bf16 v[86:89], v[162:165], v[194:197], v[86:89]
	v_mfma_f32_16x16x32_bf16 v[82:85], v[170:173], v[194:197], v[82:85]
	v_mfma_f32_16x16x32_bf16 v[70:73], v[162:165], v[202:205], v[70:73]
	v_mfma_f32_16x16x32_bf16 v[66:69], v[170:173], v[202:205], v[66:69]
	v_mfma_f32_16x16x32_bf16 v[118:121], v[166:169], v[182:185], v[118:121]
	v_mfma_f32_16x16x32_bf16 v[114:117], v[174:177], v[182:185], v[114:117]
	v_mfma_f32_16x16x32_bf16 v[102:105], v[166:169], v[190:193], v[102:105]
	v_mfma_f32_16x16x32_bf16 v[98:101], v[174:177], v[190:193], v[98:101]
	v_mfma_f32_16x16x32_bf16 v[86:89], v[166:169], v[198:201], v[86:89]
	v_mfma_f32_16x16x32_bf16 v[82:85], v[174:177], v[198:201], v[82:85]
	v_mfma_f32_16x16x32_bf16 v[70:73], v[166:169], v[222:225], v[70:73]
	v_mfma_f32_16x16x32_bf16 v[66:69], v[174:177], v[222:225], v[66:69]
	s_barrier
	s_setprio 0
	s_add_i32 s18, s47, s24
	v_lshl_add_u64 v[142:143], v[142:143], 0, s[44:45]
	s_mov_b32 m0, s18
	ds_read_b128 v[178:181], v144 offset:49152
	ds_read_b128 v[182:185], v144 offset:50176
	ds_read_b128 v[186:189], v144 offset:51200
	ds_read_b128 v[190:193], v144 offset:52224
	ds_read_b128 v[194:197], v144 offset:53248
	ds_read_b128 v[198:201], v144 offset:54272
	ds_read_b128 v[202:205], v144 offset:55296
	ds_read_b128 v[222:225], v144 offset:56320
	global_load_lds_dwordx4 v[142:143], off
	s_add_i32 m0, s18, 0x2000
	s_add_u32 s18, s20, 0xb0080
	v_lshl_add_u64 v[142:143], v[206:207], 0, s[44:45]
	s_addc_u32 s19, s21, 0
	s_add_i32 s20, s48, s24
	global_load_lds_dwordx4 v[142:143], off
	v_lshl_add_u64 v[142:143], s[18:19], 0, v[130:131]
	s_mov_b32 m0, s20
	s_nop 0
	global_load_lds_dwordx4 v[142:143], off
	v_lshl_add_u64 v[142:143], s[18:19], 0, v[132:133]
	s_add_i32 m0, s20, 0x2000
	s_nop 0
	global_load_lds_dwordx4 v[142:143], off
	v_lshl_add_u64 v[142:143], v[218:219], 0, s[44:45]
	s_mov_b32 m0, s31
	s_nop 0
	global_load_lds_dwordx4 v[142:143], off
	v_lshl_add_u64 v[142:143], v[226:227], 0, s[44:45]
	s_mov_b32 m0, s33
	s_nop 0
	global_load_lds_dwordx4 v[142:143], off
	s_waitcnt vmcnt(8)
	s_waitcnt lgkmcnt(0)
	s_setprio 1
	s_barrier
	v_mfma_f32_16x16x32_bf16 v[62:65], v[146:149], v[178:181], v[62:65]
	v_mfma_f32_16x16x32_bf16 v[58:61], v[154:157], v[178:181], v[58:61]
	v_mfma_f32_16x16x32_bf16 v[46:49], v[146:149], v[186:189], v[46:49]
	v_mfma_f32_16x16x32_bf16 v[42:45], v[154:157], v[186:189], v[42:45]
	v_mfma_f32_16x16x32_bf16 v[30:33], v[146:149], v[194:197], v[30:33]
	v_mfma_f32_16x16x32_bf16 v[26:29], v[154:157], v[194:197], v[26:29]
	v_mfma_f32_16x16x32_bf16 v[14:17], v[146:149], v[202:205], v[14:17]
	v_mfma_f32_16x16x32_bf16 v[10:13], v[154:157], v[202:205], v[10:13]
	v_mfma_f32_16x16x32_bf16 v[62:65], v[150:153], v[182:185], v[62:65]
	v_mfma_f32_16x16x32_bf16 v[58:61], v[158:161], v[182:185], v[58:61]
	v_mfma_f32_16x16x32_bf16 v[46:49], v[150:153], v[190:193], v[46:49]
	v_mfma_f32_16x16x32_bf16 v[42:45], v[158:161], v[190:193], v[42:45]
	v_mfma_f32_16x16x32_bf16 v[30:33], v[150:153], v[198:201], v[30:33]
	v_mfma_f32_16x16x32_bf16 v[26:29], v[158:161], v[198:201], v[26:29]
	v_mfma_f32_16x16x32_bf16 v[14:17], v[150:153], v[222:225], v[14:17]
	v_mfma_f32_16x16x32_bf16 v[10:13], v[158:161], v[222:225], v[10:13]
	v_mfma_f32_16x16x32_bf16 v[54:57], v[162:165], v[178:181], v[54:57]
	v_mfma_f32_16x16x32_bf16 v[50:53], v[170:173], v[178:181], v[50:53]
	v_mfma_f32_16x16x32_bf16 v[38:41], v[162:165], v[186:189], v[38:41]
	v_mfma_f32_16x16x32_bf16 v[34:37], v[170:173], v[186:189], v[34:37]
	v_mfma_f32_16x16x32_bf16 v[22:25], v[162:165], v[194:197], v[22:25]
	v_mfma_f32_16x16x32_bf16 v[18:21], v[170:173], v[194:197], v[18:21]
	v_mfma_f32_16x16x32_bf16 v[6:9], v[162:165], v[202:205], v[6:9]
	v_mfma_f32_16x16x32_bf16 v[2:5], v[170:173], v[202:205], v[2:5]
	v_mfma_f32_16x16x32_bf16 v[54:57], v[166:169], v[182:185], v[54:57]
	v_mfma_f32_16x16x32_bf16 v[50:53], v[174:177], v[182:185], v[50:53]
	v_mfma_f32_16x16x32_bf16 v[38:41], v[166:169], v[190:193], v[38:41]
	v_mfma_f32_16x16x32_bf16 v[34:37], v[174:177], v[190:193], v[34:37]
	v_mfma_f32_16x16x32_bf16 v[22:25], v[166:169], v[198:201], v[22:25]
	v_mfma_f32_16x16x32_bf16 v[18:21], v[174:177], v[198:201], v[18:21]
	v_mfma_f32_16x16x32_bf16 v[6:9], v[166:169], v[222:225], v[6:9]
	v_mfma_f32_16x16x32_bf16 v[2:5], v[174:177], v[222:225], v[2:5]
	s_barrier
	s_setprio 0
	s_add_i32 s46, s46, 2
	s_add_u32 s17, s17, 0x100
	s_addc_u32 s42, s42, 0
	s_cmp_gt_u32 s46, 41
	s_mov_b64 s[18:19], s[2:3]
	s_cbranch_scc0 .LBB0_849
	s_and_b64 vcc, exec, s[12:13]
	s_cbranch_vccz .LBB0_852
	s_barrier
